# G1 rope epilogue: dropped 14 vmcnt(0) waits that only drained the preceding stores (rope table loads are already covered by the first wait after each load batch)
# baseline (speedup 1.0000x reference)
;     DI void operator()(const pg8::f32x4 (&acc)[2][2][4][2], const pg8::Unit& u, int wr, int wc, int fr, int fq) const {
;     ...
;             for (int m = 0; m < 4; ++m) { const int row = row0 + ai * 128 + m * 16; bf16_t* rowp = O + (size_t)row * NPROJ + col0;
; #pragma unroll
;                 for (int bj = 0; bj < 2; ++bj) { f32x4 v0 = acc[ai][bj][m][0], v1 = acc[ai][bj][m][1];
;                     const bool is_q = (u.pn >= 16 && u.pn < 20), is_k = (u.pn == 20 && bj == 0);
;                     if (is_q || is_k) {
;                         const f32x4 r0 = rp[m][bj][0], r1 = rp[m][bj][1];
;                         const float sc = is_q ? 0.125f : 1.0f;
;                         f32x4 w0, w1;
;                         w0.x = (v0.x * r0.x - v0.y * r0.y) * sc; w0.y = (v0.y * r0.x + v0.x * r0.y) * sc; w0.z = (v0.z * r0.z - v0.w * r0.w) * sc; w0.w = (v0.w * r0.z + v0.z * r0.w) * sc;
;                         w1.x = (v1.x * r1.x - v1.y * r1.y) * sc; w1.y = (v1.y * r1.x + v1.x * r1.y) * sc; w1.z = (v1.z * r1.z - v1.w * r1.w) * sc; w1.w = (v1.w * r1.z + v1.z * r1.w) * sc;
;                         v0 = w0; v1 = w1;
;                     }
.LBB0_606:
	s_and_b32 s12, s48, -4
	s_cmp_eq_u32 s12, 16
	s_cselect_b64 s[8:9], -1, 0
	s_cmp_lg_u32 s12, 16
	s_cbranch_scc1 .LBB0_628
	v_pk_mul_f32 v[154:155], v[150:151], v[134:135] op_sel:[1,1] op_sel_hi:[0,1]
	v_pk_fma_f32 v[156:157], v[150:151], v[134:135], v[154:155] neg_lo:[0,0,1] neg_hi:[0,0,1]
	v_pk_fma_f32 v[150:151], v[150:151], v[134:135], v[154:155] op_sel_hi:[1,0,1]
	v_mul_f32_e32 v96, v153, v137
	v_mov_b32_e32 v157, v151
	v_pk_fma_f32 v[150:151], v[152:153], v[136:137], v[96:97] op_sel_hi:[1,1,0] neg_lo:[0,0,1] neg_hi:[0,0,1]
	v_mul_f32_e32 v96, v153, v136
	v_pk_fma_f32 v[152:153], v[152:153], v[136:137], v[96:97] op_sel:[1,0,0] op_sel_hi:[0,1,0]
	v_mov_b32_e32 v151, v153
	s_mov_b32 s12, 0x3e000000
	v_pk_mul_f32 v[154:155], v[146:147], v[130:131] op_sel:[1,1] op_sel_hi:[0,1]
	v_pk_mul_f32 v[152:153], v[150:151], s[12:13] op_sel_hi:[1,0]
	v_pk_mul_f32 v[150:151], v[156:157], s[12:13] op_sel_hi:[1,0]
	v_pk_fma_f32 v[156:157], v[146:147], v[130:131], v[154:155] neg_lo:[0,0,1] neg_hi:[0,0,1]
	v_pk_fma_f32 v[146:147], v[146:147], v[130:131], v[154:155] op_sel_hi:[1,0,1]
	v_mul_f32_e32 v96, v149, v133
	v_mov_b32_e32 v157, v147
	v_pk_fma_f32 v[146:147], v[148:149], v[132:133], v[96:97] op_sel_hi:[1,1,0] neg_lo:[0,0,1] neg_hi:[0,0,1]
	v_mul_f32_e32 v96, v149, v132
	v_pk_fma_f32 v[148:149], v[148:149], v[132:133], v[96:97] op_sel:[1,0,0] op_sel_hi:[0,1,0]
	v_mov_b32_e32 v147, v149
	v_pk_mul_f32 v[148:149], v[146:147], s[12:13] op_sel_hi:[1,0]
	v_pk_mul_f32 v[146:147], v[156:157], s[12:13] op_sel_hi:[1,0]
	v_cndmask_b32_e64 v96, 0, 1, s[10:11]
	v_cmp_ne_u32_e64 s[42:43], 1, v96
	s_andn2_b64 vcc, exec, s[10:11]
	s_cbranch_vccz .LBB0_629

;     DI void operator()(const pg8::f32x4 (&acc)[2][2][4][2], const pg8::Unit& u, int wr, int wc, int fr, int fq) const {
;     ...
;                 for (int bj = 0; bj < 2; ++bj) { f32x4 v0 = acc[ai][bj][m][0], v1 = acc[ai][bj][m][1];
;                     const bool is_q = (u.pn >= 16 && u.pn < 20), is_k = (u.pn == 20 && bj == 0);
;                     if (is_q || is_k) {
;                         const f32x4 r0 = rp[m][bj][0], r1 = rp[m][bj][1];
;                         const float sc = is_q ? 0.125f : 1.0f;
;                         f32x4 w0, w1;
;                         w0.x = (v0.x * r0.x - v0.y * r0.y) * sc; w0.y = (v0.y * r0.x + v0.x * r0.y) * sc; w0.z = (v0.z * r0.z - v0.w * r0.w) * sc; w0.w = (v0.w * r0.z + v0.z * r0.w) * sc;
;                         w1.x = (v1.x * r1.x - v1.y * r1.y) * sc; w1.y = (v1.y * r1.x + v1.x * r1.y) * sc; w1.z = (v1.z * r1.z - v1.w * r1.w) * sc; w1.w = (v1.w * r1.z + v1.z * r1.w) * sc;
;                         v0 = w0; v1 = w1;
.LBB0_609:
	s_cmp_lt_u32 s48, 20
	v_pk_mul_f32 v[146:147], v[142:143], v[110:111] op_sel:[1,1] op_sel_hi:[0,1]
	s_cselect_b64 vcc, -1, 0
	v_pk_fma_f32 v[148:149], v[142:143], v[110:111], v[146:147] neg_lo:[0,0,1] neg_hi:[0,0,1]
	v_pk_fma_f32 v[142:143], v[142:143], v[110:111], v[146:147] op_sel_hi:[1,0,1]
	v_cndmask_b32_e32 v96, 1.0, v239, vcc
	v_mov_b32_e32 v149, v143
	v_pk_mul_f32 v[142:143], v[96:97], v[148:149] op_sel_hi:[0,1]
	v_mul_f32_e32 v146, v145, v113
	v_mul_f32_e32 v148, v145, v112
	v_pk_fma_f32 v[146:147], v[144:145], v[112:113], v[146:147] op_sel_hi:[1,1,0] neg_lo:[0,0,1] neg_hi:[0,0,1]
	v_pk_fma_f32 v[144:145], v[144:145], v[112:113], v[148:149] op_sel:[1,0,0] op_sel_hi:[0,1,0]
	v_mov_b32_e32 v147, v145
	v_pk_mul_f32 v[144:145], v[96:97], v[146:147] op_sel_hi:[0,1]
	v_pk_mul_f32 v[146:147], v[138:139], v[106:107] op_sel:[1,1] op_sel_hi:[0,1]
	v_pk_fma_f32 v[148:149], v[138:139], v[106:107], v[146:147] neg_lo:[0,0,1] neg_hi:[0,0,1]
	v_pk_fma_f32 v[138:139], v[138:139], v[106:107], v[146:147] op_sel_hi:[1,0,1]
	v_mul_f32_e32 v146, v141, v109
	v_mov_b32_e32 v149, v139
	v_pk_mul_f32 v[138:139], v[96:97], v[148:149] op_sel_hi:[0,1]
	v_mul_f32_e32 v148, v141, v108
	v_pk_fma_f32 v[146:147], v[140:141], v[108:109], v[146:147] op_sel_hi:[1,1,0] neg_lo:[0,0,1] neg_hi:[0,0,1]
	v_pk_fma_f32 v[140:141], v[140:141], v[108:109], v[148:149] op_sel:[1,0,0] op_sel_hi:[0,1,0]
	v_mov_b32_e32 v147, v141
	v_pk_mul_f32 v[140:141], v[96:97], v[146:147] op_sel_hi:[0,1]

;     DI void operator()(const pg8::f32x4 (&acc)[2][2][4][2], const pg8::Unit& u, int wr, int wc, int fr, int fq) const {
;     ...
;                 for (int bj = 0; bj < 2; ++bj) { f32x4 v0 = acc[ai][bj][m][0], v1 = acc[ai][bj][m][1];
;                     const bool is_q = (u.pn >= 16 && u.pn < 20), is_k = (u.pn == 20 && bj == 0);
;                     if (is_q || is_k) {
;                         const f32x4 r0 = rp[m][bj][0], r1 = rp[m][bj][1];
;                         const float sc = is_q ? 0.125f : 1.0f;
;                         f32x4 w0, w1;
;                         w0.x = (v0.x * r0.x - v0.y * r0.y) * sc; w0.y = (v0.y * r0.x + v0.x * r0.y) * sc; w0.z = (v0.z * r0.z - v0.w * r0.w) * sc; w0.w = (v0.w * r0.z + v0.z * r0.w) * sc;
;                         w1.x = (v1.x * r1.x - v1.y * r1.y) * sc; w1.y = (v1.y * r1.x + v1.x * r1.y) * sc; w1.z = (v1.z * r1.z - v1.w * r1.w) * sc; w1.w = (v1.w * r1.z + v1.z * r1.w) * sc;
;                         v0 = w0; v1 = w1;
.LBB0_613:
	v_pk_mul_f32 v[138:139], v[126:127], v[110:111] op_sel:[1,1] op_sel_hi:[0,1]
	v_pk_fma_f32 v[140:141], v[126:127], v[110:111], v[138:139] neg_lo:[0,0,1] neg_hi:[0,0,1]
	v_pk_fma_f32 v[126:127], v[126:127], v[110:111], v[138:139] op_sel_hi:[1,0,1]
	v_mul_f32_e32 v96, v129, v113
	v_mov_b32_e32 v141, v127
	v_pk_fma_f32 v[126:127], v[128:129], v[112:113], v[96:97] op_sel_hi:[1,1,0] neg_lo:[0,0,1] neg_hi:[0,0,1]
	v_mul_f32_e32 v96, v129, v112
	v_pk_fma_f32 v[128:129], v[128:129], v[112:113], v[96:97] op_sel:[1,0,0] op_sel_hi:[0,1,0]
	v_mov_b32_e32 v127, v129
	s_mov_b32 s8, 0x3e000000
	v_pk_mul_f32 v[138:139], v[122:123], v[106:107] op_sel:[1,1] op_sel_hi:[0,1]
	v_pk_mul_f32 v[128:129], v[126:127], s[8:9] op_sel_hi:[1,0]
	v_pk_mul_f32 v[126:127], v[140:141], s[8:9] op_sel_hi:[1,0]
	v_pk_fma_f32 v[140:141], v[122:123], v[106:107], v[138:139] neg_lo:[0,0,1] neg_hi:[0,0,1]
	v_pk_fma_f32 v[122:123], v[122:123], v[106:107], v[138:139] op_sel_hi:[1,0,1]
	v_mul_f32_e32 v96, v125, v109
	v_mov_b32_e32 v141, v123
	v_pk_fma_f32 v[122:123], v[124:125], v[108:109], v[96:97] op_sel_hi:[1,1,0] neg_lo:[0,0,1] neg_hi:[0,0,1]
	v_mul_f32_e32 v96, v125, v108
	v_pk_fma_f32 v[124:125], v[124:125], v[108:109], v[96:97] op_sel:[1,0,0] op_sel_hi:[0,1,0]
	v_mov_b32_e32 v123, v125
	v_pk_mul_f32 v[124:125], v[122:123], s[8:9] op_sel_hi:[1,0]
	v_pk_mul_f32 v[122:123], v[140:141], s[8:9] op_sel_hi:[1,0]
	s_and_b64 vcc, exec, s[42:43]
	s_cbranch_vccz .LBB0_635

;     DI void operator()(const pg8::f32x4 (&acc)[2][2][4][2], const pg8::Unit& u, int wr, int wc, int fr, int fq) const {
;     ...
;                 for (int bj = 0; bj < 2; ++bj) { f32x4 v0 = acc[ai][bj][m][0], v1 = acc[ai][bj][m][1];
;                     const bool is_q = (u.pn >= 16 && u.pn < 20), is_k = (u.pn == 20 && bj == 0);
;                     if (is_q || is_k) {
;                         const f32x4 r0 = rp[m][bj][0], r1 = rp[m][bj][1];
;                         const float sc = is_q ? 0.125f : 1.0f;
;                         f32x4 w0, w1;
;                         w0.x = (v0.x * r0.x - v0.y * r0.y) * sc; w0.y = (v0.y * r0.x + v0.x * r0.y) * sc; w0.z = (v0.z * r0.z - v0.w * r0.w) * sc; w0.w = (v0.w * r0.z + v0.z * r0.w) * sc;
;                         w1.x = (v1.x * r1.x - v1.y * r1.y) * sc; w1.y = (v1.y * r1.x + v1.x * r1.y) * sc; w1.z = (v1.z * r1.z - v1.w * r1.w) * sc; w1.w = (v1.w * r1.z + v1.z * r1.w) * sc;
;                         v0 = w0; v1 = w1;
.LBB0_615:
	s_cmp_lt_u32 s48, 20
	v_pk_mul_f32 v[122:123], v[118:119], v[92:93] op_sel:[1,1] op_sel_hi:[0,1]
	s_cselect_b64 vcc, -1, 0
	v_pk_fma_f32 v[124:125], v[118:119], v[92:93], v[122:123] neg_lo:[0,0,1] neg_hi:[0,0,1]
	v_pk_fma_f32 v[118:119], v[118:119], v[92:93], v[122:123] op_sel_hi:[1,0,1]
	v_cndmask_b32_e32 v96, 1.0, v239, vcc
	v_mov_b32_e32 v125, v119
	v_pk_mul_f32 v[118:119], v[96:97], v[124:125] op_sel_hi:[0,1]
	v_mul_f32_e32 v122, v121, v95
	v_mul_f32_e32 v124, v121, v94
	v_pk_fma_f32 v[122:123], v[120:121], v[94:95], v[122:123] op_sel_hi:[1,1,0] neg_lo:[0,0,1] neg_hi:[0,0,1]
	v_pk_fma_f32 v[120:121], v[120:121], v[94:95], v[124:125] op_sel:[1,0,0] op_sel_hi:[0,1,0]
	v_mov_b32_e32 v123, v121
	v_pk_mul_f32 v[120:121], v[96:97], v[122:123] op_sel_hi:[0,1]
	v_pk_mul_f32 v[122:123], v[114:115], v[88:89] op_sel:[1,1] op_sel_hi:[0,1]
	v_pk_fma_f32 v[124:125], v[114:115], v[88:89], v[122:123] neg_lo:[0,0,1] neg_hi:[0,0,1]
	v_pk_fma_f32 v[114:115], v[114:115], v[88:89], v[122:123] op_sel_hi:[1,0,1]
	v_mul_f32_e32 v122, v117, v91
	v_mov_b32_e32 v125, v115
	v_pk_mul_f32 v[114:115], v[96:97], v[124:125] op_sel_hi:[0,1]
	v_mul_f32_e32 v124, v117, v90
	v_pk_fma_f32 v[122:123], v[116:117], v[90:91], v[122:123] op_sel_hi:[1,1,0] neg_lo:[0,0,1] neg_hi:[0,0,1]
	v_pk_fma_f32 v[116:117], v[116:117], v[90:91], v[124:125] op_sel:[1,0,0] op_sel_hi:[0,1,0]
	v_mov_b32_e32 v123, v117
	v_pk_mul_f32 v[116:117], v[96:97], v[122:123] op_sel_hi:[0,1]

;     DI void operator()(const pg8::f32x4 (&acc)[2][2][4][2], const pg8::Unit& u, int wr, int wc, int fr, int fq) const {
;     ...
;                 for (int bj = 0; bj < 2; ++bj) { f32x4 v0 = acc[ai][bj][m][0], v1 = acc[ai][bj][m][1];
;                     const bool is_q = (u.pn >= 16 && u.pn < 20), is_k = (u.pn == 20 && bj == 0);
;                     if (is_q || is_k) {
;                         const f32x4 r0 = rp[m][bj][0], r1 = rp[m][bj][1];
;                         const float sc = is_q ? 0.125f : 1.0f;
;                         f32x4 w0, w1;
;                         w0.x = (v0.x * r0.x - v0.y * r0.y) * sc; w0.y = (v0.y * r0.x + v0.x * r0.y) * sc; w0.z = (v0.z * r0.z - v0.w * r0.w) * sc; w0.w = (v0.w * r0.z + v0.z * r0.w) * sc;
;                         w1.x = (v1.x * r1.x - v1.y * r1.y) * sc; w1.y = (v1.y * r1.x + v1.x * r1.y) * sc; w1.z = (v1.z * r1.z - v1.w * r1.w) * sc; w1.w = (v1.w * r1.z + v1.z * r1.w) * sc;
;                         v0 = w0; v1 = w1;
.LBB0_619:
	v_pk_mul_f32 v[114:115], v[102:103], v[92:93] op_sel:[1,1] op_sel_hi:[0,1]
	v_pk_fma_f32 v[116:117], v[102:103], v[92:93], v[114:115] neg_lo:[0,0,1] neg_hi:[0,0,1]
	v_pk_fma_f32 v[102:103], v[102:103], v[92:93], v[114:115] op_sel_hi:[1,0,1]
	v_mul_f32_e32 v96, v105, v95
	v_mov_b32_e32 v117, v103
	v_pk_fma_f32 v[102:103], v[104:105], v[94:95], v[96:97] op_sel_hi:[1,1,0] neg_lo:[0,0,1] neg_hi:[0,0,1]
	v_mul_f32_e32 v96, v105, v94
	v_pk_fma_f32 v[104:105], v[104:105], v[94:95], v[96:97] op_sel:[1,0,0] op_sel_hi:[0,1,0]
	v_mov_b32_e32 v103, v105
	s_mov_b32 s8, 0x3e000000
	v_pk_mul_f32 v[114:115], v[98:99], v[88:89] op_sel:[1,1] op_sel_hi:[0,1]
	v_pk_mul_f32 v[104:105], v[102:103], s[8:9] op_sel_hi:[1,0]
	v_pk_mul_f32 v[102:103], v[116:117], s[8:9] op_sel_hi:[1,0]
	v_pk_fma_f32 v[116:117], v[98:99], v[88:89], v[114:115] neg_lo:[0,0,1] neg_hi:[0,0,1]
	v_pk_fma_f32 v[98:99], v[98:99], v[88:89], v[114:115] op_sel_hi:[1,0,1]
	v_mul_f32_e32 v96, v101, v91
	v_mov_b32_e32 v117, v99
	v_pk_fma_f32 v[98:99], v[100:101], v[90:91], v[96:97] op_sel_hi:[1,1,0] neg_lo:[0,0,1] neg_hi:[0,0,1]
	v_mul_f32_e32 v96, v101, v90
	v_pk_fma_f32 v[100:101], v[100:101], v[90:91], v[96:97] op_sel:[1,0,0] op_sel_hi:[0,1,0]
	v_mov_b32_e32 v99, v101
	v_pk_mul_f32 v[100:101], v[98:99], s[8:9] op_sel_hi:[1,0]
	v_pk_mul_f32 v[98:99], v[116:117], s[8:9] op_sel_hi:[1,0]
	s_and_b64 vcc, exec, s[42:43]
	s_cbranch_vccz .LBB0_641

;     DI void operator()(const pg8::f32x4 (&acc)[2][2][4][2], const pg8::Unit& u, int wr, int wc, int fr, int fq) const {
;     ...
;                 for (int bj = 0; bj < 2; ++bj) { f32x4 v0 = acc[ai][bj][m][0], v1 = acc[ai][bj][m][1];
;                     const bool is_q = (u.pn >= 16 && u.pn < 20), is_k = (u.pn == 20 && bj == 0);
;                     if (is_q || is_k) {
;                         const f32x4 r0 = rp[m][bj][0], r1 = rp[m][bj][1];
;                         const float sc = is_q ? 0.125f : 1.0f;
;                         f32x4 w0, w1;
;                         w0.x = (v0.x * r0.x - v0.y * r0.y) * sc; w0.y = (v0.y * r0.x + v0.x * r0.y) * sc; w0.z = (v0.z * r0.z - v0.w * r0.w) * sc; w0.w = (v0.w * r0.z + v0.z * r0.w) * sc;
;                         w1.x = (v1.x * r1.x - v1.y * r1.y) * sc; w1.y = (v1.y * r1.x + v1.x * r1.y) * sc; w1.z = (v1.z * r1.z - v1.w * r1.w) * sc; w1.w = (v1.w * r1.z + v1.z * r1.w) * sc;
;                         v0 = w0; v1 = w1;
.LBB0_621:
	s_cmp_lt_u32 s48, 20
	v_pk_mul_f32 v[98:99], v[84:85], v[68:69] op_sel:[1,1] op_sel_hi:[0,1]
	s_cselect_b64 vcc, -1, 0
	v_pk_fma_f32 v[100:101], v[84:85], v[68:69], v[98:99] neg_lo:[0,0,1] neg_hi:[0,0,1]
	v_pk_fma_f32 v[84:85], v[84:85], v[68:69], v[98:99] op_sel_hi:[1,0,1]
	v_cndmask_b32_e32 v96, 1.0, v239, vcc
	v_mov_b32_e32 v101, v85
	v_pk_mul_f32 v[84:85], v[96:97], v[100:101] op_sel_hi:[0,1]
	v_mul_f32_e32 v98, v87, v71
	v_mul_f32_e32 v100, v87, v70
	v_pk_fma_f32 v[98:99], v[86:87], v[70:71], v[98:99] op_sel_hi:[1,1,0] neg_lo:[0,0,1] neg_hi:[0,0,1]
	v_pk_fma_f32 v[86:87], v[86:87], v[70:71], v[100:101] op_sel:[1,0,0] op_sel_hi:[0,1,0]
	v_mov_b32_e32 v99, v87
	v_pk_mul_f32 v[86:87], v[96:97], v[98:99] op_sel_hi:[0,1]
	v_pk_mul_f32 v[98:99], v[80:81], v[64:65] op_sel:[1,1] op_sel_hi:[0,1]
	v_pk_fma_f32 v[100:101], v[80:81], v[64:65], v[98:99] neg_lo:[0,0,1] neg_hi:[0,0,1]
	v_pk_fma_f32 v[80:81], v[80:81], v[64:65], v[98:99] op_sel_hi:[1,0,1]
	v_mul_f32_e32 v98, v83, v67
	v_mov_b32_e32 v101, v81
	v_pk_mul_f32 v[80:81], v[96:97], v[100:101] op_sel_hi:[0,1]
	v_mul_f32_e32 v100, v83, v66
	v_pk_fma_f32 v[98:99], v[82:83], v[66:67], v[98:99] op_sel_hi:[1,1,0] neg_lo:[0,0,1] neg_hi:[0,0,1]
	v_pk_fma_f32 v[82:83], v[82:83], v[66:67], v[100:101] op_sel:[1,0,0] op_sel_hi:[0,1,0]
	v_mov_b32_e32 v99, v83
	v_pk_mul_f32 v[82:83], v[96:97], v[98:99] op_sel_hi:[0,1]

;     DI void operator()(const pg8::f32x4 (&acc)[2][2][4][2], const pg8::Unit& u, int wr, int wc, int fr, int fq) const {
;     ...
;                 for (int bj = 0; bj < 2; ++bj) { f32x4 v0 = acc[ai][bj][m][0], v1 = acc[ai][bj][m][1];
;                     const bool is_q = (u.pn >= 16 && u.pn < 20), is_k = (u.pn == 20 && bj == 0);
;                     if (is_q || is_k) {
;                         const f32x4 r0 = rp[m][bj][0], r1 = rp[m][bj][1];
;                         const float sc = is_q ? 0.125f : 1.0f;
;                         f32x4 w0, w1;
;                         w0.x = (v0.x * r0.x - v0.y * r0.y) * sc; w0.y = (v0.y * r0.x + v0.x * r0.y) * sc; w0.z = (v0.z * r0.z - v0.w * r0.w) * sc; w0.w = (v0.w * r0.z + v0.z * r0.w) * sc;
;                         w1.x = (v1.x * r1.x - v1.y * r1.y) * sc; w1.y = (v1.y * r1.x + v1.x * r1.y) * sc; w1.z = (v1.z * r1.z - v1.w * r1.w) * sc; w1.w = (v1.w * r1.z + v1.z * r1.w) * sc;
;                         v0 = w0; v1 = w1;
.LBB0_625:
	v_pk_mul_f32 v[80:81], v[76:77], v[68:69] op_sel:[1,1] op_sel_hi:[0,1]
	v_pk_fma_f32 v[82:83], v[76:77], v[68:69], v[80:81] neg_lo:[0,0,1] neg_hi:[0,0,1]
	v_pk_fma_f32 v[76:77], v[76:77], v[68:69], v[80:81] op_sel_hi:[1,0,1]
	v_mul_f32_e32 v80, v79, v70
	v_mul_f32_e32 v76, v79, v71
	v_mov_b32_e32 v83, v77
	v_pk_fma_f32 v[76:77], v[78:79], v[70:71], v[76:77] op_sel_hi:[1,1,0] neg_lo:[0,0,1] neg_hi:[0,0,1]
	v_pk_fma_f32 v[78:79], v[78:79], v[70:71], v[80:81] op_sel:[1,0,0] op_sel_hi:[0,1,0]
	v_mov_b32_e32 v77, v79
	s_mov_b32 s8, 0x3e000000
	v_pk_mul_f32 v[80:81], v[72:73], v[64:65] op_sel:[1,1] op_sel_hi:[0,1]
	v_pk_mul_f32 v[78:79], v[76:77], s[8:9] op_sel_hi:[1,0]
	v_pk_mul_f32 v[76:77], v[82:83], s[8:9] op_sel_hi:[1,0]
	v_pk_fma_f32 v[82:83], v[72:73], v[64:65], v[80:81] neg_lo:[0,0,1] neg_hi:[0,0,1]
	v_pk_fma_f32 v[72:73], v[72:73], v[64:65], v[80:81] op_sel_hi:[1,0,1]
	v_mul_f32_e32 v80, v75, v66
	v_mul_f32_e32 v72, v75, v67
	v_mov_b32_e32 v83, v73
	v_pk_fma_f32 v[72:73], v[74:75], v[66:67], v[72:73] op_sel_hi:[1,1,0] neg_lo:[0,0,1] neg_hi:[0,0,1]
	v_pk_fma_f32 v[74:75], v[74:75], v[66:67], v[80:81] op_sel:[1,0,0] op_sel_hi:[0,1,0]
	v_mov_b32_e32 v73, v75
	v_pk_mul_f32 v[74:75], v[72:73], s[8:9] op_sel_hi:[1,0]
	v_pk_mul_f32 v[72:73], v[82:83], s[8:9] op_sel_hi:[1,0]
	s_and_b64 vcc, exec, s[42:43]
	s_cbranch_vccz .LBB0_647

;     DI void operator()(const pg8::f32x4 (&acc)[2][2][4][2], const pg8::Unit& u, int wr, int wc, int fr, int fq) const {
;     ...
;                 for (int bj = 0; bj < 2; ++bj) { f32x4 v0 = acc[ai][bj][m][0], v1 = acc[ai][bj][m][1];
;                     const bool is_q = (u.pn >= 16 && u.pn < 20), is_k = (u.pn == 20 && bj == 0);
;                     if (is_q || is_k) {
;                         const f32x4 r0 = rp[m][bj][0], r1 = rp[m][bj][1];
;                         const float sc = is_q ? 0.125f : 1.0f;
;                         f32x4 w0, w1;
;                         w0.x = (v0.x * r0.x - v0.y * r0.y) * sc; w0.y = (v0.y * r0.x + v0.x * r0.y) * sc; w0.z = (v0.z * r0.z - v0.w * r0.w) * sc; w0.w = (v0.w * r0.z + v0.z * r0.w) * sc;
;                         w1.x = (v1.x * r1.x - v1.y * r1.y) * sc; w1.y = (v1.y * r1.x + v1.x * r1.y) * sc; w1.z = (v1.z * r1.z - v1.w * r1.w) * sc; w1.w = (v1.w * r1.z + v1.z * r1.w) * sc;
;                         v0 = w0; v1 = w1;
.LBB0_653:
	v_pk_mul_f32 v[56:57], v[52:53], v[134:135] op_sel:[1,1] op_sel_hi:[0,1]
	v_pk_fma_f32 v[58:59], v[52:53], v[134:135], v[56:57] neg_lo:[0,0,1] neg_hi:[0,0,1]
	v_pk_fma_f32 v[52:53], v[52:53], v[134:135], v[56:57] op_sel_hi:[1,0,1]
	v_mul_f32_e32 v56, v55, v136
	v_mul_f32_e32 v52, v55, v137
	v_mov_b32_e32 v59, v53
	v_pk_fma_f32 v[52:53], v[54:55], v[136:137], v[52:53] op_sel_hi:[1,1,0] neg_lo:[0,0,1] neg_hi:[0,0,1]
	v_pk_fma_f32 v[54:55], v[54:55], v[136:137], v[56:57] op_sel:[1,0,0] op_sel_hi:[0,1,0]
	v_mov_b32_e32 v53, v55
	s_mov_b32 s8, 0x3e000000
	v_pk_mul_f32 v[56:57], v[48:49], v[130:131] op_sel:[1,1] op_sel_hi:[0,1]
	v_pk_mul_f32 v[54:55], v[52:53], s[8:9] op_sel_hi:[1,0]
	v_pk_mul_f32 v[52:53], v[58:59], s[8:9] op_sel_hi:[1,0]
	v_pk_fma_f32 v[58:59], v[48:49], v[130:131], v[56:57] neg_lo:[0,0,1] neg_hi:[0,0,1]
	v_pk_fma_f32 v[48:49], v[48:49], v[130:131], v[56:57] op_sel_hi:[1,0,1]
	v_mul_f32_e32 v56, v51, v132
	v_mul_f32_e32 v48, v51, v133
	v_mov_b32_e32 v59, v49
	v_pk_fma_f32 v[48:49], v[50:51], v[132:133], v[48:49] op_sel_hi:[1,1,0] neg_lo:[0,0,1] neg_hi:[0,0,1]
	v_pk_fma_f32 v[50:51], v[50:51], v[132:133], v[56:57] op_sel:[1,0,0] op_sel_hi:[0,1,0]
	v_mov_b32_e32 v49, v51
	v_pk_mul_f32 v[50:51], v[48:49], s[8:9] op_sel_hi:[1,0]
	v_pk_mul_f32 v[48:49], v[58:59], s[8:9] op_sel_hi:[1,0]
	s_and_b64 vcc, exec, s[42:43]
	s_cbranch_vccz .LBB0_678

;     DI void operator()(const pg8::f32x4 (&acc)[2][2][4][2], const pg8::Unit& u, int wr, int wc, int fr, int fq) const {
;     ...
;                 for (int bj = 0; bj < 2; ++bj) { f32x4 v0 = acc[ai][bj][m][0], v1 = acc[ai][bj][m][1];
;                     const bool is_q = (u.pn >= 16 && u.pn < 20), is_k = (u.pn == 20 && bj == 0);
;                     if (is_q || is_k) {
;                         const f32x4 r0 = rp[m][bj][0], r1 = rp[m][bj][1];
;                         const float sc = is_q ? 0.125f : 1.0f;
;                         f32x4 w0, w1;
;                         w0.x = (v0.x * r0.x - v0.y * r0.y) * sc; w0.y = (v0.y * r0.x + v0.x * r0.y) * sc; w0.z = (v0.z * r0.z - v0.w * r0.w) * sc; w0.w = (v0.w * r0.z + v0.z * r0.w) * sc;
;                         w1.x = (v1.x * r1.x - v1.y * r1.y) * sc; w1.y = (v1.y * r1.x + v1.x * r1.y) * sc; w1.z = (v1.z * r1.z - v1.w * r1.w) * sc; w1.w = (v1.w * r1.z + v1.z * r1.w) * sc;
;                         v0 = w0; v1 = w1;
.LBB0_655:
	s_cmp_lt_u32 s48, 20
	v_pk_mul_f32 v[50:51], v[44:45], v[110:111] op_sel:[1,1] op_sel_hi:[0,1]
	s_cselect_b64 vcc, -1, 0
	v_pk_fma_f32 v[52:53], v[44:45], v[110:111], v[50:51] neg_lo:[0,0,1] neg_hi:[0,0,1]
	v_pk_fma_f32 v[44:45], v[44:45], v[110:111], v[50:51] op_sel_hi:[1,0,1]
	v_cndmask_b32_e32 v48, 1.0, v239, vcc
	v_mov_b32_e32 v53, v45
	v_pk_mul_f32 v[44:45], v[48:49], v[52:53] op_sel_hi:[0,1]
	v_mul_f32_e32 v50, v47, v113
	v_mul_f32_e32 v52, v47, v112
	v_pk_fma_f32 v[50:51], v[46:47], v[112:113], v[50:51] op_sel_hi:[1,1,0] neg_lo:[0,0,1] neg_hi:[0,0,1]
	v_pk_fma_f32 v[46:47], v[46:47], v[112:113], v[52:53] op_sel:[1,0,0] op_sel_hi:[0,1,0]
	v_mov_b32_e32 v51, v47
	v_pk_mul_f32 v[46:47], v[48:49], v[50:51] op_sel_hi:[0,1]
	v_pk_mul_f32 v[50:51], v[40:41], v[106:107] op_sel:[1,1] op_sel_hi:[0,1]
	v_pk_fma_f32 v[52:53], v[40:41], v[106:107], v[50:51] neg_lo:[0,0,1] neg_hi:[0,0,1]
	v_pk_fma_f32 v[40:41], v[40:41], v[106:107], v[50:51] op_sel_hi:[1,0,1]
	v_mul_f32_e32 v50, v43, v109
	v_mov_b32_e32 v53, v41
	v_pk_mul_f32 v[40:41], v[48:49], v[52:53] op_sel_hi:[0,1]
	v_mul_f32_e32 v52, v43, v108
	v_pk_fma_f32 v[50:51], v[42:43], v[108:109], v[50:51] op_sel_hi:[1,1,0] neg_lo:[0,0,1] neg_hi:[0,0,1]
	v_pk_fma_f32 v[42:43], v[42:43], v[108:109], v[52:53] op_sel:[1,0,0] op_sel_hi:[0,1,0]
	v_mov_b32_e32 v51, v43
	v_pk_mul_f32 v[42:43], v[48:49], v[50:51] op_sel_hi:[0,1]

;     DI void operator()(const pg8::f32x4 (&acc)[2][2][4][2], const pg8::Unit& u, int wr, int wc, int fr, int fq) const {
;     ...
;                 for (int bj = 0; bj < 2; ++bj) { f32x4 v0 = acc[ai][bj][m][0], v1 = acc[ai][bj][m][1];
;                     const bool is_q = (u.pn >= 16 && u.pn < 20), is_k = (u.pn == 20 && bj == 0);
;                     if (is_q || is_k) {
;                         const f32x4 r0 = rp[m][bj][0], r1 = rp[m][bj][1];
;                         const float sc = is_q ? 0.125f : 1.0f;
;                         f32x4 w0, w1;
;                         w0.x = (v0.x * r0.x - v0.y * r0.y) * sc; w0.y = (v0.y * r0.x + v0.x * r0.y) * sc; w0.z = (v0.z * r0.z - v0.w * r0.w) * sc; w0.w = (v0.w * r0.z + v0.z * r0.w) * sc;
;                         w1.x = (v1.x * r1.x - v1.y * r1.y) * sc; w1.y = (v1.y * r1.x + v1.x * r1.y) * sc; w1.z = (v1.z * r1.z - v1.w * r1.w) * sc; w1.w = (v1.w * r1.z + v1.z * r1.w) * sc;
;                         v0 = w0; v1 = w1;
.LBB0_659:
	v_pk_mul_f32 v[40:41], v[36:37], v[110:111] op_sel:[1,1] op_sel_hi:[0,1]
	v_pk_fma_f32 v[42:43], v[36:37], v[110:111], v[40:41] neg_lo:[0,0,1] neg_hi:[0,0,1]
	v_pk_fma_f32 v[36:37], v[36:37], v[110:111], v[40:41] op_sel_hi:[1,0,1]
	v_mul_f32_e32 v40, v39, v112
	v_mul_f32_e32 v36, v39, v113
	v_mov_b32_e32 v43, v37
	v_pk_fma_f32 v[36:37], v[38:39], v[112:113], v[36:37] op_sel_hi:[1,1,0] neg_lo:[0,0,1] neg_hi:[0,0,1]
	v_pk_fma_f32 v[38:39], v[38:39], v[112:113], v[40:41] op_sel:[1,0,0] op_sel_hi:[0,1,0]
	v_mov_b32_e32 v37, v39
	s_mov_b32 s8, 0x3e000000
	v_pk_mul_f32 v[40:41], v[32:33], v[106:107] op_sel:[1,1] op_sel_hi:[0,1]
	v_pk_mul_f32 v[38:39], v[36:37], s[8:9] op_sel_hi:[1,0]
	v_pk_mul_f32 v[36:37], v[42:43], s[8:9] op_sel_hi:[1,0]
	v_pk_fma_f32 v[42:43], v[32:33], v[106:107], v[40:41] neg_lo:[0,0,1] neg_hi:[0,0,1]
	v_pk_fma_f32 v[32:33], v[32:33], v[106:107], v[40:41] op_sel_hi:[1,0,1]
	v_mul_f32_e32 v40, v35, v108
	v_mul_f32_e32 v32, v35, v109
	v_mov_b32_e32 v43, v33
	v_pk_fma_f32 v[32:33], v[34:35], v[108:109], v[32:33] op_sel_hi:[1,1,0] neg_lo:[0,0,1] neg_hi:[0,0,1]
	v_pk_fma_f32 v[34:35], v[34:35], v[108:109], v[40:41] op_sel:[1,0,0] op_sel_hi:[0,1,0]
	v_mov_b32_e32 v33, v35
	v_pk_mul_f32 v[34:35], v[32:33], s[8:9] op_sel_hi:[1,0]
	v_pk_mul_f32 v[32:33], v[42:43], s[8:9] op_sel_hi:[1,0]
	s_and_b64 vcc, exec, s[42:43]
	s_cbranch_vccz .LBB0_684

;     DI void operator()(const pg8::f32x4 (&acc)[2][2][4][2], const pg8::Unit& u, int wr, int wc, int fr, int fq) const {
;     ...
;                 for (int bj = 0; bj < 2; ++bj) { f32x4 v0 = acc[ai][bj][m][0], v1 = acc[ai][bj][m][1];
;                     const bool is_q = (u.pn >= 16 && u.pn < 20), is_k = (u.pn == 20 && bj == 0);
;                     if (is_q || is_k) {
;                         const f32x4 r0 = rp[m][bj][0], r1 = rp[m][bj][1];
;                         const float sc = is_q ? 0.125f : 1.0f;
;                         f32x4 w0, w1;
;                         w0.x = (v0.x * r0.x - v0.y * r0.y) * sc; w0.y = (v0.y * r0.x + v0.x * r0.y) * sc; w0.z = (v0.z * r0.z - v0.w * r0.w) * sc; w0.w = (v0.w * r0.z + v0.z * r0.w) * sc;
;                         w1.x = (v1.x * r1.x - v1.y * r1.y) * sc; w1.y = (v1.y * r1.x + v1.x * r1.y) * sc; w1.z = (v1.z * r1.z - v1.w * r1.w) * sc; w1.w = (v1.w * r1.z + v1.z * r1.w) * sc;
;                         v0 = w0; v1 = w1;
.LBB0_661:
	s_cmp_lt_u32 s48, 20
	v_pk_mul_f32 v[34:35], v[28:29], v[92:93] op_sel:[1,1] op_sel_hi:[0,1]
	s_cselect_b64 vcc, -1, 0
	v_pk_fma_f32 v[36:37], v[28:29], v[92:93], v[34:35] neg_lo:[0,0,1] neg_hi:[0,0,1]
	v_pk_fma_f32 v[28:29], v[28:29], v[92:93], v[34:35] op_sel_hi:[1,0,1]
	v_cndmask_b32_e32 v32, 1.0, v239, vcc
	v_mov_b32_e32 v37, v29
	v_pk_mul_f32 v[28:29], v[32:33], v[36:37] op_sel_hi:[0,1]
	v_mul_f32_e32 v34, v31, v95
	v_mul_f32_e32 v36, v31, v94
	v_pk_fma_f32 v[34:35], v[30:31], v[94:95], v[34:35] op_sel_hi:[1,1,0] neg_lo:[0,0,1] neg_hi:[0,0,1]
	v_pk_fma_f32 v[30:31], v[30:31], v[94:95], v[36:37] op_sel:[1,0,0] op_sel_hi:[0,1,0]
	v_mov_b32_e32 v35, v31
	v_pk_mul_f32 v[30:31], v[32:33], v[34:35] op_sel_hi:[0,1]
	v_pk_mul_f32 v[34:35], v[24:25], v[88:89] op_sel:[1,1] op_sel_hi:[0,1]
	v_pk_fma_f32 v[36:37], v[24:25], v[88:89], v[34:35] neg_lo:[0,0,1] neg_hi:[0,0,1]
	v_pk_fma_f32 v[24:25], v[24:25], v[88:89], v[34:35] op_sel_hi:[1,0,1]
	v_mul_f32_e32 v34, v27, v91
	v_mov_b32_e32 v37, v25
	v_pk_mul_f32 v[24:25], v[32:33], v[36:37] op_sel_hi:[0,1]
	v_mul_f32_e32 v36, v27, v90
	v_pk_fma_f32 v[34:35], v[26:27], v[90:91], v[34:35] op_sel_hi:[1,1,0] neg_lo:[0,0,1] neg_hi:[0,0,1]
	v_pk_fma_f32 v[26:27], v[26:27], v[90:91], v[36:37] op_sel:[1,0,0] op_sel_hi:[0,1,0]
	v_mov_b32_e32 v35, v27
	v_pk_mul_f32 v[26:27], v[32:33], v[34:35] op_sel_hi:[0,1]

;     DI void operator()(const pg8::f32x4 (&acc)[2][2][4][2], const pg8::Unit& u, int wr, int wc, int fr, int fq) const {
;     ...
;                 for (int bj = 0; bj < 2; ++bj) { f32x4 v0 = acc[ai][bj][m][0], v1 = acc[ai][bj][m][1];
;                     const bool is_q = (u.pn >= 16 && u.pn < 20), is_k = (u.pn == 20 && bj == 0);
;                     if (is_q || is_k) {
;                         const f32x4 r0 = rp[m][bj][0], r1 = rp[m][bj][1];
;                         const float sc = is_q ? 0.125f : 1.0f;
;                         f32x4 w0, w1;
;                         w0.x = (v0.x * r0.x - v0.y * r0.y) * sc; w0.y = (v0.y * r0.x + v0.x * r0.y) * sc; w0.z = (v0.z * r0.z - v0.w * r0.w) * sc; w0.w = (v0.w * r0.z + v0.z * r0.w) * sc;
;                         w1.x = (v1.x * r1.x - v1.y * r1.y) * sc; w1.y = (v1.y * r1.x + v1.x * r1.y) * sc; w1.z = (v1.z * r1.z - v1.w * r1.w) * sc; w1.w = (v1.w * r1.z + v1.z * r1.w) * sc;
;                         v0 = w0; v1 = w1;
.LBB0_665:
	v_pk_mul_f32 v[24:25], v[20:21], v[92:93] op_sel:[1,1] op_sel_hi:[0,1]
	v_pk_fma_f32 v[26:27], v[20:21], v[92:93], v[24:25] neg_lo:[0,0,1] neg_hi:[0,0,1]
	v_pk_fma_f32 v[20:21], v[20:21], v[92:93], v[24:25] op_sel_hi:[1,0,1]
	v_mul_f32_e32 v24, v23, v94
	v_mul_f32_e32 v20, v23, v95
	v_mov_b32_e32 v27, v21
	v_pk_fma_f32 v[20:21], v[22:23], v[94:95], v[20:21] op_sel_hi:[1,1,0] neg_lo:[0,0,1] neg_hi:[0,0,1]
	v_pk_fma_f32 v[22:23], v[22:23], v[94:95], v[24:25] op_sel:[1,0,0] op_sel_hi:[0,1,0]
	v_mov_b32_e32 v21, v23
	s_mov_b32 s8, 0x3e000000
	v_pk_mul_f32 v[24:25], v[16:17], v[88:89] op_sel:[1,1] op_sel_hi:[0,1]
	v_pk_mul_f32 v[22:23], v[20:21], s[8:9] op_sel_hi:[1,0]
	v_pk_mul_f32 v[20:21], v[26:27], s[8:9] op_sel_hi:[1,0]
	v_pk_fma_f32 v[26:27], v[16:17], v[88:89], v[24:25] neg_lo:[0,0,1] neg_hi:[0,0,1]
	v_pk_fma_f32 v[16:17], v[16:17], v[88:89], v[24:25] op_sel_hi:[1,0,1]
	v_mul_f32_e32 v24, v19, v90
	v_mul_f32_e32 v16, v19, v91
	v_mov_b32_e32 v27, v17
	v_pk_fma_f32 v[16:17], v[18:19], v[90:91], v[16:17] op_sel_hi:[1,1,0] neg_lo:[0,0,1] neg_hi:[0,0,1]
	v_pk_fma_f32 v[18:19], v[18:19], v[90:91], v[24:25] op_sel:[1,0,0] op_sel_hi:[0,1,0]
	v_mov_b32_e32 v17, v19
	v_pk_mul_f32 v[18:19], v[16:17], s[8:9] op_sel_hi:[1,0]
	v_pk_mul_f32 v[16:17], v[26:27], s[8:9] op_sel_hi:[1,0]
	s_and_b64 vcc, exec, s[42:43]
	s_cbranch_vccz .LBB0_690

;     DI void operator()(const pg8::f32x4 (&acc)[2][2][4][2], const pg8::Unit& u, int wr, int wc, int fr, int fq) const {
;     ...
;                 for (int bj = 0; bj < 2; ++bj) { f32x4 v0 = acc[ai][bj][m][0], v1 = acc[ai][bj][m][1];
;                     const bool is_q = (u.pn >= 16 && u.pn < 20), is_k = (u.pn == 20 && bj == 0);
;                     if (is_q || is_k) {
;                         const f32x4 r0 = rp[m][bj][0], r1 = rp[m][bj][1];
;                         const float sc = is_q ? 0.125f : 1.0f;
;                         f32x4 w0, w1;
;                         w0.x = (v0.x * r0.x - v0.y * r0.y) * sc; w0.y = (v0.y * r0.x + v0.x * r0.y) * sc; w0.z = (v0.z * r0.z - v0.w * r0.w) * sc; w0.w = (v0.w * r0.z + v0.z * r0.w) * sc;
;                         w1.x = (v1.x * r1.x - v1.y * r1.y) * sc; w1.y = (v1.y * r1.x + v1.x * r1.y) * sc; w1.z = (v1.z * r1.z - v1.w * r1.w) * sc; w1.w = (v1.w * r1.z + v1.z * r1.w) * sc;
;                         v0 = w0; v1 = w1;
.LBB0_667:
	s_cmp_lt_u32 s48, 20
	v_pk_mul_f32 v[18:19], v[12:13], v[68:69] op_sel:[1,1] op_sel_hi:[0,1]
	s_cselect_b64 vcc, -1, 0
	v_pk_fma_f32 v[20:21], v[12:13], v[68:69], v[18:19] neg_lo:[0,0,1] neg_hi:[0,0,1]
	v_pk_fma_f32 v[12:13], v[12:13], v[68:69], v[18:19] op_sel_hi:[1,0,1]
	v_cndmask_b32_e32 v16, 1.0, v239, vcc
	v_mov_b32_e32 v21, v13
	v_pk_mul_f32 v[12:13], v[16:17], v[20:21] op_sel_hi:[0,1]
	v_mul_f32_e32 v18, v15, v71
	v_mul_f32_e32 v20, v15, v70
	v_pk_fma_f32 v[18:19], v[14:15], v[70:71], v[18:19] op_sel_hi:[1,1,0] neg_lo:[0,0,1] neg_hi:[0,0,1]
	v_pk_fma_f32 v[14:15], v[14:15], v[70:71], v[20:21] op_sel:[1,0,0] op_sel_hi:[0,1,0]
	v_mov_b32_e32 v19, v15
	v_pk_mul_f32 v[14:15], v[16:17], v[18:19] op_sel_hi:[0,1]
	v_pk_mul_f32 v[18:19], v[8:9], v[64:65] op_sel:[1,1] op_sel_hi:[0,1]
	v_pk_fma_f32 v[20:21], v[8:9], v[64:65], v[18:19] neg_lo:[0,0,1] neg_hi:[0,0,1]
	v_pk_fma_f32 v[8:9], v[8:9], v[64:65], v[18:19] op_sel_hi:[1,0,1]
	v_mul_f32_e32 v18, v11, v67
	v_mov_b32_e32 v21, v9
	v_pk_mul_f32 v[8:9], v[16:17], v[20:21] op_sel_hi:[0,1]
	v_mul_f32_e32 v20, v11, v66
	v_pk_fma_f32 v[18:19], v[10:11], v[66:67], v[18:19] op_sel_hi:[1,1,0] neg_lo:[0,0,1] neg_hi:[0,0,1]
	v_pk_fma_f32 v[10:11], v[10:11], v[66:67], v[20:21] op_sel:[1,0,0] op_sel_hi:[0,1,0]
	v_mov_b32_e32 v19, v11
	v_pk_mul_f32 v[10:11], v[16:17], v[18:19] op_sel_hi:[0,1]

;     DI void operator()(const pg8::f32x4 (&acc)[2][2][4][2], const pg8::Unit& u, int wr, int wc, int fr, int fq) const {
;     ...
;                 for (int bj = 0; bj < 2; ++bj) { f32x4 v0 = acc[ai][bj][m][0], v1 = acc[ai][bj][m][1];
;                     const bool is_q = (u.pn >= 16 && u.pn < 20), is_k = (u.pn == 20 && bj == 0);
;                     if (is_q || is_k) {
;                         const f32x4 r0 = rp[m][bj][0], r1 = rp[m][bj][1];
;                         const float sc = is_q ? 0.125f : 1.0f;
;                         f32x4 w0, w1;
;                         w0.x = (v0.x * r0.x - v0.y * r0.y) * sc; w0.y = (v0.y * r0.x + v0.x * r0.y) * sc; w0.z = (v0.z * r0.z - v0.w * r0.w) * sc; w0.w = (v0.w * r0.z + v0.z * r0.w) * sc;
;                         w1.x = (v1.x * r1.x - v1.y * r1.y) * sc; w1.y = (v1.y * r1.x + v1.x * r1.y) * sc; w1.z = (v1.z * r1.z - v1.w * r1.w) * sc; w1.w = (v1.w * r1.z + v1.z * r1.w) * sc;
;                         v0 = w0; v1 = w1;
.LBB0_671:
	v_pk_mul_f32 v[8:9], v[4:5], v[68:69] op_sel:[1,1] op_sel_hi:[0,1]
	v_pk_fma_f32 v[10:11], v[4:5], v[68:69], v[8:9] neg_lo:[0,0,1] neg_hi:[0,0,1]
	v_pk_fma_f32 v[4:5], v[4:5], v[68:69], v[8:9] op_sel_hi:[1,0,1]
	v_mul_f32_e32 v8, v7, v70
	v_mul_f32_e32 v4, v7, v71
	v_mov_b32_e32 v11, v5
	v_pk_fma_f32 v[4:5], v[6:7], v[70:71], v[4:5] op_sel_hi:[1,1,0] neg_lo:[0,0,1] neg_hi:[0,0,1]
	v_pk_fma_f32 v[6:7], v[6:7], v[70:71], v[8:9] op_sel:[1,0,0] op_sel_hi:[0,1,0]
	v_mov_b32_e32 v5, v7
	s_mov_b32 s8, 0x3e000000
	v_pk_mul_f32 v[8:9], v[0:1], v[64:65] op_sel:[1,1] op_sel_hi:[0,1]
	v_pk_mul_f32 v[6:7], v[4:5], s[8:9] op_sel_hi:[1,0]
	v_pk_mul_f32 v[4:5], v[10:11], s[8:9] op_sel_hi:[1,0]
	v_pk_fma_f32 v[10:11], v[0:1], v[64:65], v[8:9] neg_lo:[0,0,1] neg_hi:[0,0,1]
	v_pk_fma_f32 v[0:1], v[0:1], v[64:65], v[8:9] op_sel_hi:[1,0,1]
	v_mul_f32_e32 v8, v3, v66
	v_mul_f32_e32 v0, v3, v67
	v_mov_b32_e32 v11, v1
	v_pk_fma_f32 v[0:1], v[2:3], v[66:67], v[0:1] op_sel_hi:[1,1,0] neg_lo:[0,0,1] neg_hi:[0,0,1]
	v_pk_fma_f32 v[2:3], v[2:3], v[66:67], v[8:9] op_sel:[1,0,0] op_sel_hi:[0,1,0]
	v_mov_b32_e32 v1, v3
	v_pk_mul_f32 v[2:3], v[0:1], s[8:9] op_sel_hi:[1,0]
	v_pk_mul_f32 v[0:1], v[10:11], s[8:9] op_sel_hi:[1,0]
	s_and_b64 vcc, exec, s[42:43]
	s_cbranch_vccz .LBB0_696
